# stack with the prompt-item wave 4-7 stagger doubled (s_sleep 24 instead of 12)
# speedup vs baseline: 1.0195x; 1.0029x over previous
; template <bool SAMPLE> ...
;     ...
; #pragma unroll
;     for (int d0 = 0; d0 < 4; ++d0) { const f32x4 g0 = *(const f32x4*)(qg + d0 * 16 + hi * 8), g1 = *(const f32x4*)(qg + d0 * 16 + hi * 8 + 4);
;         q[d0][0] *= rstd * g0.x; q[d0][1] *= rstd * g0.y; q[d0][2] *= rstd * g0.z; q[d0][3] *= rstd * g0.w; q[d0][4] *= rstd * g1.x; q[d0][5] *= rstd * g1.y; q[d0][6] *= rstd * g1.z; q[d0][7] *= rstd * g1.w; }
; __device__ __forceinline__ void attn_prompt_item(const Args& a, int l, int item, LAS unsigned char* lds, int tid, int lane, int wave) {
;     ...
;     __syncthreads();
;     attn_tile32<false>(qw0, zw0, Y, tab, qg, sinks, Kl + 32 * qt0 * 144, Vl + 32 * qt0 * 64, 16384, wsf, ost, rowq0, headw, b * 128 + qt0 * 32, (b == 0) ? 4 - qt0 : 0, lane);
;     attn_tile32<false>(qw1, zw1, Y, tab, qg, sinks, Kl + 32 * (qt0 + 1) * 144, Vl + 32 * (qt0 + 1) * 64, 16384, wsf, ost, rowq0 + 32, headw, b * 128 + qt0 * 32 + 32, (b == 0) ? 3 - qt0 : 0, lane);
.LBB0_475:
	s_or_b64 exec, exec, s[0:1]
	v_cmp_lt_i32_e32 vcc, v220, v214
	v_and_b32_e32 v172, 32, v132
	s_waitcnt lgkmcnt(0)
	v_cndmask_b32_e32 v16, v213, v220, vcc
	s_barrier
	v_lshlrev_b32_e32 v127, 2, v16
	global_load_dwordx4 v[16:19], v172, s[62:63]
	global_load_dwordx4 v[20:23], v172, s[62:63] offset:16
	global_load_dwordx4 v[24:27], v172, s[62:63] offset:64
	global_load_dwordx4 v[28:31], v172, s[62:63] offset:80
	global_load_dwordx4 v[32:35], v172, s[62:63] offset:128
	global_load_dwordx4 v[36:39], v172, s[62:63] offset:144
	global_load_dwordx4 v[40:43], v172, s[62:63] offset:192
	global_load_dwordx4 v[44:47], v172, s[62:63] offset:208
	v_readfirstlane_b32 s0, v208
	s_nop 3
	s_cmpk_lt_u32 s0, 0x100
	s_cbranch_scc1 .Lstg_skip
	s_sleep 24
